# GQA main loop per-group softmax/PV pipeline, second schedule: two partial row sums, adds placed after each group's MFMA pair
# speedup vs baseline: 1.0065x; 1.0065x over previous
; template <int D>
; DI void attn_pass(const bfr* __restrict__ P, int b, int tq_wave, int qcol, int kcol, int vcol, int key0, int nkt, char* smem, f32x16 (&o)[2]) {
;     ...
;   for (int kt = 0; kt < nkt; ++kt) {
;     bfr* sK = sbase + (kt & 1) * 9216;
;     bfr* sV = sK + 64 * 72;
;     { int c = gt, row = c >> 3, kc = c & 7; *(u32x4*)(sK + row * KP + kc * 8) = kreg[0]; }
;     for (int i = 0; i < 1; ++i) {
;       int c = gt, row = c >> 3, kc = c & 7;
;       unsigned wds[4] = {vreg[i].x, vreg[i].y, vreg[i].z, vreg[i].w};
; #pragma unroll
;       for (int e = 0; e < 4; ++e) {
;         sV[(kc * 8 + 2 * e) * 72 + (row ^ (kc << 3))] = (bfr)(wds[e] & 0xffffu);
;         sV[(kc * 8 + 2 * e + 1) * 72 + (row ^ (kc << 3))] = (bfr)(wds[e] >> 16);
;       }
;     }
;     __syncthreads();
;     if (kt + 1 < nkt) {
;       const bfr* Pn = Pb + (size_t)(kt + 1) * 64 * PW;
;       { int c = gt, row = c >> 3, kc = c & 7; kreg[0] = *(const u32x4*)(Pn + (size_t)row * PW + kcol + kc * 8); vreg[0] = *(const u32x4*)(Pn + (size_t)row * PW + vcol + kc * 8); }
;     }
;     f32x16 s[2];
; #pragma unroll
;     for (int t2 = 0; t2 < 2; ++t2) {
; #pragma unroll
;       for (int i = 0; i < 16; ++i) s[t2][i] = 0.f;
; #pragma unroll
;       for (int ks = 0; ks < KS; ++ks) {
;         bf16x8 a = *(const bf16x8*)(sK + (t2 * 32 + r) * KP + ks * 16 + h * 8);
;         s[t2] = MFMA32(a, qf[ks], s[t2]);
;       }
;     }
;     float mx = s[0][0];
; #pragma unroll
;     for (int i = 0; i < 16; ++i) { mx = fmaxf(mx, s[0][i]); mx = fmaxf(mx, s[1][i]); }
;     mx = fmaxf(mx, __shfl_xor(mx, 32));
;     float mnew = fmaxf(mrun, mx);
;     float alpha = __builtin_amdgcn_exp2f(mrun - mnew);
;     mrun = mnew;
;     float ps = 0.f;
; #pragma unroll
;     for (int i = 0; i < 16; ++i) {
;       s[0][i] = __builtin_amdgcn_exp2f(s[0][i] - mnew); ps += s[0][i];
;       s[1][i] = __builtin_amdgcn_exp2f(s[1][i] - mnew); ps += s[1][i];
;     }
;     lsum = lsum * alpha + ps;
; #pragma unroll
;     for (int i = 0; i < 16; ++i) { accO[0][i] *= alpha; accO[1][i] *= alpha; }
; #pragma unroll
;     for (int t2 = 0; t2 < 2; ++t2)
; #pragma unroll
;       for (int j = 0; j < 2; ++j) {
;         unsigned pk[4];
; #pragma unroll
;         for (int e = 0; e < 4; ++e) pk[e] = pack2(s[t2][8 * j + 2 * e], s[t2][8 * j + 2 * e + 1]);
;         u32x4 pku = {pk[0], pk[1], pk[2], pk[3]};
.LBB0_412:
	s_bitcmp1_b32 s8, 0
	s_cselect_b32 s9, 0x4800, 0
	s_add_i32 s9, s9, 0
	v_add3_u32 v32, s9, v115, v90
	v_add_u32_e32 v121, s9, v114
	v_mov_b32_e32 v120, v113
	s_waitcnt vmcnt(1)
	ds_write_b128 v32, v[84:87]
	v_add3_u32 v32, s9, v117, v118
	v_add3_u32 v33, s9, v118, v117
	v_add_u32_e32 v113, v121, v152
	s_waitcnt vmcnt(0)
	ds_write_b16 v32, v80 offset:9216
	ds_write_b16_d16_hi v33, v80 offset:9360
	ds_write_b16 v32, v81 offset:9504
	ds_write_b16_d16_hi v33, v81 offset:9648
	ds_write_b16 v32, v82 offset:9792
	ds_write_b16_d16_hi v33, v82 offset:9936
	ds_write_b16 v32, v83 offset:10080
	ds_write_b16_d16_hi v33, v83 offset:10224
	s_waitcnt lgkmcnt(0)
	s_barrier
	global_load_dwordx4 v[84:87], v[92:93], off
	global_load_dwordx4 v[80:83], v[94:95], off
	ds_read_b128 v[126:129], v113
	ds_read_b128 v[130:133], v113 offset:32
	ds_read_b128 v[134:137], v113 offset:64
	ds_read_b128 v[138:141], v113 offset:96
	ds_read_b128 v[142:145], v113 offset:4608
	ds_read_b128 v[146:149], v113 offset:4640
	ds_read_b128 v[156:159], v113 offset:4672
	ds_read_b128 v[164:167], v113 offset:4704
	v_mov_b32_e32 v96, v119
	s_waitcnt lgkmcnt(7)
	v_mfma_f32_32x32x16_bf16 v[32:47], v[126:129], v[76:79], 0
	s_add_i32 s8, s8, 1
	s_waitcnt lgkmcnt(6)
	v_mfma_f32_32x32x16_bf16 v[32:47], v[130:133], v[72:75], v[32:47]
	v_lshl_add_u64 v[92:93], v[92:93], 0, s[10:11]
	s_waitcnt lgkmcnt(5)
	v_mfma_f32_32x32x16_bf16 v[32:47], v[134:137], v[68:71], v[32:47]
	v_lshl_add_u64 v[94:95], v[94:95], 0, s[10:11]
	s_waitcnt lgkmcnt(4)
	v_mfma_f32_32x32x16_bf16 v[32:47], v[138:141], v[64:67], v[32:47]
	s_cmp_lg_u32 s8, 35
	s_waitcnt lgkmcnt(3)
	v_mfma_f32_32x32x16_bf16 v[48:63], v[142:145], v[76:79], 0
	s_waitcnt lgkmcnt(2)
	v_mfma_f32_32x32x16_bf16 v[48:63], v[146:149], v[72:75], v[48:63]
	s_waitcnt lgkmcnt(1)
	v_mfma_f32_32x32x16_bf16 v[48:63], v[156:159], v[68:71], v[48:63]
	s_waitcnt lgkmcnt(0)
	v_mfma_f32_32x32x16_bf16 v[48:63], v[164:167], v[64:67], v[48:63]
	v_add_u32_e32 v154, s9, v116
	v_lshl_add_u32 v168, v112, 1, v121
	v_lshl_add_u32 v169, v111, 1, v121
	v_lshl_add_u32 v170, v110, 1, v154
	v_lshl_add_u32 v171, v109, 1, v154
	v_lshl_add_u32 v172, v108, 1, v121
	v_lshl_add_u32 v173, v107, 1, v121
	v_lshl_add_u32 v174, v106, 1, v154
	v_lshl_add_u32 v175, v105, 1, v154
	v_lshl_add_u32 v176, v104, 1, v121
	v_lshl_add_u32 v177, v103, 1, v154
	v_lshl_add_u32 v178, v102, 1, v154
	v_lshl_add_u32 v179, v100, 1, v121
	v_lshl_add_u32 v180, v101, 1, v121
	v_lshl_add_u32 v181, v99, 1, v154
	v_lshl_add_u32 v160, v98, 1, v154
	v_max_f32_e32 v119, v32, v32
	v_max_f32_e32 v113, v48, v48
	v_max_f32_e32 v113, v119, v113
	v_max3_f32 v113, v113, v33, v49
	v_max3_f32 v113, v113, v34, v50
	v_max3_f32 v113, v113, v35, v51
	v_max3_f32 v113, v113, v36, v52
	v_max3_f32 v113, v113, v37, v53
	v_max3_f32 v113, v113, v38, v54
	v_max3_f32 v113, v113, v39, v55
	v_max3_f32 v113, v113, v40, v56
	v_max3_f32 v113, v113, v41, v57
	v_max3_f32 v113, v113, v42, v58
	v_max3_f32 v113, v113, v43, v59
	v_max3_f32 v113, v113, v44, v60
	v_max3_f32 v113, v113, v45, v61
	v_max3_f32 v113, v113, v46, v62
	v_max3_f32 v113, v113, v47, v63
	ds_bpermute_b32 v119, v91, v113
	s_waitcnt lgkmcnt(0)
	ds_read_b64 v[126:127], v168 offset:9216
	ds_read_b64 v[128:129], v169 offset:9216
	ds_read_b64 v[130:131], v170 offset:9216
	ds_read_b64 v[132:133], v171 offset:9216
	ds_read_b64 v[134:135], v172 offset:9216
	ds_read_b64 v[136:137], v173 offset:9216
	ds_read_b64 v[138:139], v174 offset:9216
	ds_read_b64 v[140:141], v175 offset:9216
	v_max3_f32 v119, v96, v113, v119
	v_sub_f32_e32 v96, v96, v119
	v_exp_f32_e32 v96, v96
	v_pk_add_f32 v[32:33], v[32:33], v[118:119] op_sel:[0,1] op_sel_hi:[1,1] neg_lo:[0,1] neg_hi:[0,1]
	v_pk_add_f32 v[34:35], v[34:35], v[118:119] op_sel:[0,1] op_sel_hi:[1,1] neg_lo:[0,1] neg_hi:[0,1]
	v_pk_add_f32 v[36:37], v[36:37], v[118:119] op_sel:[0,1] op_sel_hi:[1,1] neg_lo:[0,1] neg_hi:[0,1]
	v_pk_add_f32 v[38:39], v[38:39], v[118:119] op_sel:[0,1] op_sel_hi:[1,1] neg_lo:[0,1] neg_hi:[0,1]
	v_exp_f32_e32 v32, v32
	v_pk_mul_f32 v[30:31], v[30:31], v[96:97] op_sel_hi:[1,0]
	v_exp_f32_e32 v33, v33
	v_pk_mul_f32 v[28:29], v[28:29], v[96:97] op_sel_hi:[1,0]
	v_exp_f32_e32 v34, v34
	v_pk_mul_f32 v[26:27], v[26:27], v[96:97] op_sel_hi:[1,0]
	v_exp_f32_e32 v35, v35
	v_pk_mul_f32 v[24:25], v[24:25], v[96:97] op_sel_hi:[1,0]
	v_exp_f32_e32 v36, v36
	v_pk_mul_f32 v[22:23], v[22:23], v[96:97] op_sel_hi:[1,0]
	v_exp_f32_e32 v37, v37
	v_pk_mul_f32 v[20:21], v[20:21], v[96:97] op_sel_hi:[1,0]
	v_exp_f32_e32 v38, v38
	v_pk_mul_f32 v[18:19], v[18:19], v[96:97] op_sel_hi:[1,0]
	v_exp_f32_e32 v39, v39
	v_pk_mul_f32 v[16:17], v[16:17], v[96:97] op_sel_hi:[1,0]
	s_waitcnt lgkmcnt(4)
	ds_read_b64 v[142:143], v168 offset:9280
	ds_read_b64 v[144:145], v176 offset:9216
	ds_read_b64 v[146:147], v177 offset:9216
	ds_read_b64 v[148:149], v178 offset:9216
	ds_read_b64 v[156:157], v179 offset:9216
	ds_read_b64 v[158:159], v180 offset:9216
	ds_read_b64 v[164:165], v181 offset:9216
	ds_read_b64 v[166:167], v160 offset:9216
	v_pk_mul_f32 v[14:15], v[14:15], v[96:97] op_sel_hi:[1,0]
	v_add_f32_e32 v113, v32, v34
	v_pk_mul_f32 v[12:13], v[12:13], v[96:97] op_sel_hi:[1,0]
	v_add_f32_e32 v122, v33, v35
	v_pk_mul_f32 v[10:11], v[10:11], v[96:97] op_sel_hi:[1,0]
	v_add_f32_e32 v113, v36, v113
	v_pk_mul_f32 v[8:9], v[8:9], v[96:97] op_sel_hi:[1,0]
	v_add_f32_e32 v122, v37, v122
	v_pk_mul_f32 v[6:7], v[6:7], v[96:97] op_sel_hi:[1,0]
	v_add_f32_e32 v113, v38, v113
	v_pk_mul_f32 v[4:5], v[4:5], v[96:97] op_sel_hi:[1,0]
	v_add_f32_e32 v122, v39, v122
	v_pk_mul_f32 v[2:3], v[2:3], v[96:97] op_sel_hi:[1,0]
	v_pk_mul_f32 v[0:1], v[0:1], v[96:97] op_sel_hi:[1,0]
	v_cvt_pk_bf16_f32 v32, v32, v33
	v_cvt_pk_bf16_f32 v33, v34, v35
	v_cvt_pk_bf16_f32 v34, v36, v37
	v_cvt_pk_bf16_f32 v35, v38, v39
	v_pk_add_f32 v[40:41], v[40:41], v[118:119] op_sel:[0,1] op_sel_hi:[1,1] neg_lo:[0,1] neg_hi:[0,1]
	v_pk_add_f32 v[42:43], v[42:43], v[118:119] op_sel:[0,1] op_sel_hi:[1,1] neg_lo:[0,1] neg_hi:[0,1]
	v_pk_add_f32 v[44:45], v[44:45], v[118:119] op_sel:[0,1] op_sel_hi:[1,1] neg_lo:[0,1] neg_hi:[0,1]
	v_pk_add_f32 v[46:47], v[46:47], v[118:119] op_sel:[0,1] op_sel_hi:[1,1] neg_lo:[0,1] neg_hi:[0,1]
	s_waitcnt lgkmcnt(8)
; template <int D>
; DI void attn_pass(const bfr* __restrict__ P, int b, int tq_wave, int qcol, int kcol, int vcol, int key0, int nkt, char* smem, f32x16 (&o)[2]) {
;     ...
;   for (int kt = 0; kt < nkt; ++kt) {
;     bfr* sK = sbase + (kt & 1) * 9216;
;     bfr* sV = sK + 64 * 72;
;     { int c = gt, row = c >> 3, kc = c & 7; *(u32x4*)(sK + row * KP + kc * 8) = kreg[0]; }
;     for (int i = 0; i < 1; ++i) {
;       int c = gt, row = c >> 3, kc = c & 7;
;       unsigned wds[4] = {vreg[i].x, vreg[i].y, vreg[i].z, vreg[i].w};
; #pragma unroll
;       for (int e = 0; e < 4; ++e) {
;         sV[(kc * 8 + 2 * e) * 72 + (row ^ (kc << 3))] = (bfr)(wds[e] & 0xffffu);
;         sV[(kc * 8 + 2 * e + 1) * 72 + (row ^ (kc << 3))] = (bfr)(wds[e] >> 16);
;       }
;     }
;     __syncthreads();
;     if (kt + 1 < nkt) {
;       const bfr* Pn = Pb + (size_t)(kt + 1) * 64 * PW;
;       { int c = gt, row = c >> 3, kc = c & 7; kreg[0] = *(const u32x4*)(Pn + (size_t)row * PW + kcol + kc * 8); vreg[0] = *(const u32x4*)(Pn + (size_t)row * PW + vcol + kc * 8); }
;     }
;     f32x16 s[2];
; #pragma unroll
;     for (int t2 = 0; t2 < 2; ++t2) {
; #pragma unroll
;     ...
;     float ps = 0.f;
; #pragma unroll
;     for (int i = 0; i < 16; ++i) {
;       s[0][i] = __builtin_amdgcn_exp2f(s[0][i] - mnew); ps += s[0][i];
;       s[1][i] = __builtin_amdgcn_exp2f(s[1][i] - mnew); ps += s[1][i];
;     }
;     lsum = lsum * alpha + ps;
; #pragma unroll
;     for (int i = 0; i < 16; ++i) { accO[0][i] *= alpha; accO[1][i] *= alpha; }
; #pragma unroll
;     for (int t2 = 0; t2 < 2; ++t2)
; #pragma unroll
;       for (int j = 0; j < 2; ++j) {
;         unsigned pk[4];
; #pragma unroll
;         for (int e = 0; e < 4; ++e) pk[e] = pack2(s[t2][8 * j + 2 * e], s[t2][8 * j + 2 * e + 1]);
;         u32x4 pku = {pk[0], pk[1], pk[2], pk[3]};
;         bf16x8 pf = __builtin_bit_cast(bf16x8, pku);
; #pragma unroll
;         for (int dt = 0; dt < 2; ++dt) {
;           const int vsw = (((dt * 32 + r) >> 3) & 7) << 3;
;           const bfr* vrow = sV + (dt * 32 + r) * 72;
;           s16x4 lo = *(const s16x4*)(vrow + ((t2 * 32 + 16 * j + 4 * h) ^ vsw));
;           s16x4 hi = *(const s16x4*)(vrow + ((t2 * 32 + 16 * j + 4 * h + 8) ^ vsw));
;           bf16x8 vf = __builtin_shufflevector(lo, hi, 0, 1, 2, 3, 4, 5, 6, 7);
;           accO[dt] = MFMA32(vf, pf, accO[dt]);
;         }
;       }
	v_mfma_f32_32x32x16_bf16 v[16:31], v[126:129], v[32:35], v[16:31]
	v_mfma_f32_32x32x16_bf16 v[0:15], v[130:133], v[32:35], v[0:15]
	v_exp_f32_e32 v40, v40
	v_exp_f32_e32 v41, v41
	v_exp_f32_e32 v42, v42
	v_exp_f32_e32 v43, v43
	v_exp_f32_e32 v44, v44
	v_exp_f32_e32 v45, v45
	v_exp_f32_e32 v46, v46
	v_exp_f32_e32 v47, v47
	v_pk_add_f32 v[48:49], v[48:49], v[118:119] op_sel:[0,1] op_sel_hi:[1,1] neg_lo:[0,1] neg_hi:[0,1]
	v_pk_add_f32 v[50:51], v[50:51], v[118:119] op_sel:[0,1] op_sel_hi:[1,1] neg_lo:[0,1] neg_hi:[0,1]
	v_pk_add_f32 v[52:53], v[52:53], v[118:119] op_sel:[0,1] op_sel_hi:[1,1] neg_lo:[0,1] neg_hi:[0,1]
	v_pk_add_f32 v[54:55], v[54:55], v[118:119] op_sel:[0,1] op_sel_hi:[1,1] neg_lo:[0,1] neg_hi:[0,1]
	v_cvt_pk_bf16_f32 v32, v40, v41
	v_cvt_pk_bf16_f32 v33, v42, v43
	v_cvt_pk_bf16_f32 v34, v44, v45
	v_cvt_pk_bf16_f32 v35, v46, v47
	s_nop 1
	v_mfma_f32_32x32x16_bf16 v[16:31], v[134:137], v[32:35], v[16:31]
	v_mfma_f32_32x32x16_bf16 v[0:15], v[138:141], v[32:35], v[0:15]
	v_add_f32_e32 v113, v40, v113
	v_add_f32_e32 v122, v41, v122
	v_add_f32_e32 v113, v42, v113
	v_add_f32_e32 v122, v43, v122
	v_add_f32_e32 v113, v44, v113
	v_add_f32_e32 v122, v45, v122
	v_add_f32_e32 v113, v46, v113
	v_add_f32_e32 v122, v47, v122
	v_exp_f32_e32 v48, v48
	v_exp_f32_e32 v49, v49
	v_exp_f32_e32 v50, v50
	v_exp_f32_e32 v51, v51
	v_exp_f32_e32 v52, v52
	v_exp_f32_e32 v53, v53
	v_exp_f32_e32 v54, v54
	v_exp_f32_e32 v55, v55
	v_pk_add_f32 v[56:57], v[56:57], v[118:119] op_sel:[0,1] op_sel_hi:[1,1] neg_lo:[0,1] neg_hi:[0,1]
	v_pk_add_f32 v[58:59], v[58:59], v[118:119] op_sel:[0,1] op_sel_hi:[1,1] neg_lo:[0,1] neg_hi:[0,1]
	v_pk_add_f32 v[60:61], v[60:61], v[118:119] op_sel:[0,1] op_sel_hi:[1,1] neg_lo:[0,1] neg_hi:[0,1]
	v_pk_add_f32 v[62:63], v[62:63], v[118:119] op_sel:[0,1] op_sel_hi:[1,1] neg_lo:[0,1] neg_hi:[0,1]
	v_cvt_pk_bf16_f32 v32, v48, v49
	v_cvt_pk_bf16_f32 v33, v50, v51
	v_cvt_pk_bf16_f32 v34, v52, v53
	v_cvt_pk_bf16_f32 v35, v54, v55
	s_nop 1
	s_waitcnt lgkmcnt(4)
	v_mfma_f32_32x32x16_bf16 v[16:31], v[142:145], v[32:35], v[16:31]
	v_mfma_f32_32x32x16_bf16 v[0:15], v[146:149], v[32:35], v[0:15]
	v_add_f32_e32 v113, v48, v113
	v_add_f32_e32 v122, v49, v122
	v_add_f32_e32 v113, v50, v113
	v_add_f32_e32 v122, v51, v122
	v_add_f32_e32 v113, v52, v113
	v_add_f32_e32 v122, v53, v122
	v_add_f32_e32 v113, v54, v113
	v_add_f32_e32 v122, v55, v122
	v_exp_f32_e32 v56, v56
	v_exp_f32_e32 v57, v57
	v_exp_f32_e32 v58, v58
	v_exp_f32_e32 v59, v59
	v_exp_f32_e32 v60, v60
	v_exp_f32_e32 v61, v61
	v_exp_f32_e32 v62, v62
	v_exp_f32_e32 v63, v63
	v_cvt_pk_bf16_f32 v32, v56, v57
	v_cvt_pk_bf16_f32 v33, v58, v59
	v_cvt_pk_bf16_f32 v34, v60, v61
	v_cvt_pk_bf16_f32 v35, v62, v63
	s_nop 1
	s_waitcnt lgkmcnt(0)
	v_mfma_f32_32x32x16_bf16 v[16:31], v[156:159], v[32:35], v[16:31]
	v_mfma_f32_32x32x16_bf16 v[0:15], v[164:167], v[32:35], v[0:15]
	v_add_f32_e32 v113, v56, v113
	v_add_f32_e32 v122, v57, v122
	v_add_f32_e32 v113, v58, v113
	v_add_f32_e32 v122, v59, v122
	v_add_f32_e32 v113, v60, v113
	v_add_f32_e32 v122, v61, v122
	v_add_f32_e32 v113, v62, v113
	v_add_f32_e32 v122, v63, v122
	v_add_f32_e32 v113, v113, v122
	v_fmac_f32_e32 v113, v120, v96
	s_cbranch_scc1 .LBB0_412
	v_add3_u32 v32, 0, v115, v90
	s_waitcnt vmcnt(1)
	ds_write_b128 v32, v[84:87] offset:18432
	v_add3_u32 v32, 0, v117, v118
	v_add3_u32 v33, 0, v118, v117
	s_waitcnt vmcnt(0)
	ds_write_b16 v32, v80 offset:27648
	ds_write_b16_d16_hi v33, v80 offset:27792
	ds_write_b16 v32, v81 offset:27936
	ds_write_b16_d16_hi v33, v81 offset:28080
	ds_write_b16 v32, v82 offset:28224
	ds_write_b16_d16_hi v33, v82 offset:28368
	ds_write_b16 v32, v83 offset:28512
	ds_write_b16_d16_hi v33, v83 offset:28656
	v_add_u32_e32 v80, 0, v114
	v_add_u32_e32 v81, v80, v152
	s_waitcnt lgkmcnt(0)
	s_barrier
	ds_read_b128 v[32:35], v81 offset:18432
	ds_read_b128 v[48:51], v81 offset:18464
	s_waitcnt lgkmcnt(1)
	v_mfma_f32_32x32x16_bf16 v[32:47], v[32:35], v[76:79], 0
	v_lshlrev_b32_e32 v152, 1, v88
	s_waitcnt lgkmcnt(0)
	v_mfma_f32_32x32x16_bf16 v[32:47], v[48:51], v[72:75], v[32:47]
	ds_read_b128 v[48:51], v81 offset:18496
	s_waitcnt lgkmcnt(0)
	v_mfma_f32_32x32x16_bf16 v[32:47], v[48:51], v[68:71], v[32:47]
	ds_read_b128 v[48:51], v81 offset:18528
	s_waitcnt lgkmcnt(0)
	v_mfma_f32_32x32x16_bf16 v[32:47], v[48:51], v[64:67], v[32:47]
	ds_read_b128 v[48:51], v81 offset:23040
	s_waitcnt lgkmcnt(0)
	v_mfma_f32_32x32x16_bf16 v[48:63], v[48:51], v[76:79], 0
	ds_read_b128 v[76:79], v81 offset:23072
	s_waitcnt lgkmcnt(0)
	v_mfma_f32_32x32x16_bf16 v[48:63], v[76:79], v[72:75], v[48:63]
	ds_read_b128 v[72:75], v81 offset:23104
	s_waitcnt lgkmcnt(0)
	v_mfma_f32_32x32x16_bf16 v[48:63], v[72:75], v[68:71], v[48:63]
	ds_read_b128 v[68:71], v81 offset:23136
	s_waitcnt lgkmcnt(0)
	v_mfma_f32_32x32x16_bf16 v[48:63], v[68:71], v[64:67], v[48:63]
	v_max_f32_e32 v65, v32, v32
	v_lshl_add_u32 v66, v112, 1, v80
	v_add_u32_e32 v67, 0x1200, v80
	s_nop 8
	v_max_f32_e32 v64, v48, v48
	v_max_f32_e32 v64, v65, v64
	v_max3_f32 v64, v64, v33, v49
	v_max3_f32 v64, v64, v34, v50
	v_max3_f32 v64, v64, v35, v51
	v_max3_f32 v64, v64, v36, v52
	v_max3_f32 v64, v64, v37, v53
	v_max3_f32 v64, v64, v38, v54
	v_max3_f32 v64, v64, v39, v55
	v_max3_f32 v64, v64, v40, v56
	v_max3_f32 v64, v64, v41, v57
	v_max3_f32 v64, v64, v42, v58
	v_max3_f32 v64, v64, v43, v59
	v_max3_f32 v64, v64, v44, v60
	v_max3_f32 v64, v64, v45, v61
	v_max3_f32 v64, v64, v46, v62
	v_max3_f32 v64, v64, v47, v63
	ds_bpermute_b32 v65, v91, v64
	s_waitcnt lgkmcnt(0)
; #define MFMA32(a, b, c) __builtin_amdgcn_mfma_f32_32x32x16_bf16((a), (b), (c), 0, 0, 0)
; DI unsigned pack2(float a, float b) { unsigned r; asm volatile("v_cvt_pk_bf16_f32 %0, %1, %2" : "=v"(r) : "v"(a), "v"(b)); return r; }
; template <int D>
; DI void attn_pass(const bfr* __restrict__ P, int b, int tq_wave, int qcol, int kcol, int vcol, int key0, int nkt, char* smem, f32x16 (&o)[2]) {
;     ...
;     float mx = s[0][0];
; #pragma unroll
;     for (int i = 0; i < 16; ++i) { mx = fmaxf(mx, s[0][i]); mx = fmaxf(mx, s[1][i]); }
;     mx = fmaxf(mx, __shfl_xor(mx, 32));
;     float mnew = fmaxf(mrun, mx);
;     float alpha = __builtin_amdgcn_exp2f(mrun - mnew);
;     mrun = mnew;
;     float ps = 0.f;
; #pragma unroll
;     for (int i = 0; i < 16; ++i) {
;       s[0][i] = __builtin_amdgcn_exp2f(s[0][i] - mnew); ps += s[0][i];
;       s[1][i] = __builtin_amdgcn_exp2f(s[1][i] - mnew); ps += s[1][i];
;     }
;     lsum = lsum * alpha + ps;
; #pragma unroll
;     for (int i = 0; i < 16; ++i) { accO[0][i] *= alpha; accO[1][i] *= alpha; }
; #pragma unroll
;     for (int t2 = 0; t2 < 2; ++t2)
; #pragma unroll
;       for (int j = 0; j < 2; ++j) {
;         unsigned pk[4];
; #pragma unroll
;         for (int e = 0; e < 4; ++e) pk[e] = pack2(s[t2][8 * j + 2 * e], s[t2][8 * j + 2 * e + 1]);
;         u32x4 pku = {pk[0], pk[1], pk[2], pk[3]};
;         bf16x8 pf = __builtin_bit_cast(bf16x8, pku);
; #pragma unroll
;         for (int dt = 0; dt < 2; ++dt) {
;           const int vsw = (((dt * 32 + r) >> 3) & 7) << 3;
;           const bfr* vrow = sV + (dt * 32 + r) * 72;
;           s16x4 lo = *(const s16x4*)(vrow + ((t2 * 32 + 16 * j + 4 * h) ^ vsw));
;           s16x4 hi = *(const s16x4*)(vrow + ((t2 * 32 + 16 * j + 4 * h + 8) ^ vsw));
;           bf16x8 vf = __builtin_shufflevector(lo, hi, 0, 1, 2, 3, 4, 5, 6, 7);
;           accO[dt] = MFMA32(vf, pf, accO[dt]);
;         }
;       }
	v_max3_f32 v65, v119, v64, v65
	v_sub_f32_e32 v64, v119, v65
	v_sub_f32_e32 v32, v32, v65
	v_exp_f32_e32 v64, v64
	v_exp_f32_e32 v32, v32
	v_sub_f32_e32 v48, v48, v65
	v_exp_f32_e32 v48, v48
	v_sub_f32_e32 v33, v33, v65
	v_exp_f32_e32 v33, v33
	v_sub_f32_e32 v49, v49, v65
	v_exp_f32_e32 v49, v49
	v_sub_f32_e32 v34, v34, v65
	v_exp_f32_e32 v34, v34
	v_sub_f32_e32 v50, v50, v65
	v_sub_f32_e32 v35, v35, v65
	v_sub_f32_e32 v51, v51, v65
	v_sub_f32_e32 v36, v36, v65
	v_sub_f32_e32 v52, v52, v65
	v_sub_f32_e32 v37, v37, v65
	v_sub_f32_e32 v53, v53, v65
	v_sub_f32_e32 v38, v38, v65
	v_sub_f32_e32 v54, v54, v65
	v_sub_f32_e32 v39, v39, v65
	v_sub_f32_e32 v55, v55, v65
	v_sub_f32_e32 v40, v40, v65
	v_sub_f32_e32 v56, v56, v65
	v_sub_f32_e32 v41, v41, v65
	v_sub_f32_e32 v57, v57, v65
	v_sub_f32_e32 v42, v42, v65
	v_sub_f32_e32 v58, v58, v65
	v_sub_f32_e32 v43, v43, v65
	v_sub_f32_e32 v59, v59, v65
	v_sub_f32_e32 v44, v44, v65
	v_sub_f32_e32 v60, v60, v65
	v_sub_f32_e32 v45, v45, v65
	v_sub_f32_e32 v61, v61, v65
	v_sub_f32_e32 v46, v46, v65
	v_sub_f32_e32 v62, v62, v65
	v_sub_f32_e32 v47, v47, v65
	v_sub_f32_e32 v63, v63, v65
	v_pk_mul_f32 v[30:31], v[30:31], v[64:65] op_sel_hi:[1,0]
	v_pk_mul_f32 v[28:29], v[28:29], v[64:65] op_sel_hi:[1,0]
	v_pk_mul_f32 v[26:27], v[26:27], v[64:65] op_sel_hi:[1,0]
	v_pk_mul_f32 v[24:25], v[24:25], v[64:65] op_sel_hi:[1,0]
	v_pk_mul_f32 v[22:23], v[22:23], v[64:65] op_sel_hi:[1,0]
	v_pk_mul_f32 v[20:21], v[20:21], v[64:65] op_sel_hi:[1,0]
	v_pk_mul_f32 v[18:19], v[18:19], v[64:65] op_sel_hi:[1,0]
	v_pk_mul_f32 v[16:17], v[16:17], v[64:65] op_sel_hi:[1,0]
	v_pk_mul_f32 v[14:15], v[14:15], v[64:65] op_sel_hi:[1,0]
	v_pk_mul_f32 v[12:13], v[12:13], v[64:65] op_sel_hi:[1,0]
	v_pk_mul_f32 v[10:11], v[10:11], v[64:65] op_sel_hi:[1,0]
	v_pk_mul_f32 v[8:9], v[8:9], v[64:65] op_sel_hi:[1,0]
	v_pk_mul_f32 v[6:7], v[6:7], v[64:65] op_sel_hi:[1,0]
	v_pk_mul_f32 v[4:5], v[4:5], v[64:65] op_sel_hi:[1,0]
	v_pk_mul_f32 v[2:3], v[2:3], v[64:65] op_sel_hi:[1,0]
	v_pk_mul_f32 v[0:1], v[0:1], v[64:65] op_sel_hi:[1,0]
	v_add_f32_e32 v65, 0, v32
	v_exp_f32_e32 v50, v50
	v_add_f32_e32 v65, v48, v65
	v_exp_f32_e32 v35, v35
	v_add_f32_e32 v65, v33, v65
	v_exp_f32_e32 v51, v51
	v_add_f32_e32 v65, v49, v65
	v_exp_f32_e32 v36, v36
	v_add_f32_e32 v65, v34, v65
	v_exp_f32_e32 v52, v52
	v_add_f32_e32 v65, v50, v65
	v_exp_f32_e32 v37, v37
	v_add_f32_e32 v65, v35, v65
	v_exp_f32_e32 v53, v53
	v_add_f32_e32 v65, v51, v65
	v_exp_f32_e32 v38, v38
	v_add_f32_e32 v65, v36, v65
	v_exp_f32_e32 v54, v54
	v_add_f32_e32 v65, v52, v65
	v_exp_f32_e32 v39, v39
	v_add_f32_e32 v65, v37, v65
	v_add_f32_e32 v65, v53, v65
	v_add_f32_e32 v65, v38, v65
	v_add_f32_e32 v65, v54, v65
	v_cvt_pk_bf16_f32 v32, v32, v33
	v_cvt_pk_bf16_f32 v33, v34, v35
	v_cvt_pk_bf16_f32 v34, v36, v37
	v_cvt_pk_bf16_f32 v35, v38, v39
	v_lshl_add_u32 v38, v111, 1, v80
	v_add_f32_e32 v65, v39, v65
	ds_read_b64 v[36:37], v66 offset:27648
	ds_read_b64 v[38:39], v38 offset:27648
	s_waitcnt lgkmcnt(0)
	v_mfma_f32_32x32x16_bf16 v[16:31], v[36:39], v[32:35], v[16:31]
	v_lshl_add_u32 v36, v110, 1, v67
	v_lshl_add_u32 v38, v109, 1, v67
	ds_read_b64 v[36:37], v36 offset:27648
	ds_read_b64 v[38:39], v38 offset:27648
	v_exp_f32_e32 v40, v40
	v_exp_f32_e32 v41, v41
	v_exp_f32_e32 v42, v42
	s_waitcnt lgkmcnt(0)
	v_mfma_f32_32x32x16_bf16 v[0:15], v[36:39], v[32:35], v[0:15]
	v_lshl_add_u32 v36, v108, 1, v80
	v_lshl_add_u32 v38, v107, 1, v80
	v_exp_f32_e32 v43, v43
	v_exp_f32_e32 v44, v44
	v_exp_f32_e32 v45, v45
	v_exp_f32_e32 v46, v46
	v_exp_f32_e32 v47, v47
	v_cvt_pk_bf16_f32 v32, v40, v41
	v_cvt_pk_bf16_f32 v33, v42, v43
	v_cvt_pk_bf16_f32 v34, v44, v45
	v_cvt_pk_bf16_f32 v35, v46, v47
	ds_read_b64 v[36:37], v36 offset:27648
	ds_read_b64 v[38:39], v38 offset:27648
	s_waitcnt lgkmcnt(0)
	v_mfma_f32_32x32x16_bf16 v[16:31], v[36:39], v[32:35], v[16:31]
	v_lshl_add_u32 v36, v106, 1, v67
	v_lshl_add_u32 v38, v105, 1, v67
	ds_read_b64 v[36:37], v36 offset:27648
	ds_read_b64 v[38:39], v38 offset:27648
	v_exp_f32_e32 v55, v55
	v_exp_f32_e32 v56, v56
	v_exp_f32_e32 v57, v57
	s_waitcnt lgkmcnt(0)
	v_mfma_f32_32x32x16_bf16 v[0:15], v[36:39], v[32:35], v[0:15]
	v_lshl_add_u32 v38, v104, 1, v80
	v_cvt_pk_bf16_f32 v32, v48, v49
	v_cvt_pk_bf16_f32 v33, v50, v51
	v_cvt_pk_bf16_f32 v34, v52, v53
	v_cvt_pk_bf16_f32 v35, v54, v55
	ds_read_b64 v[36:37], v66 offset:27712
	ds_read_b64 v[38:39], v38 offset:27648
	s_waitcnt lgkmcnt(0)
; DI unsigned pack2(float a, float b) { unsigned r; asm volatile("v_cvt_pk_bf16_f32 %0, %1, %2" : "=v"(r) : "v"(a), "v"(b)); return r; }
; template <int D>
; DI void attn_pass(const bfr* __restrict__ P, int b, int tq_wave, int qcol, int kcol, int vcol, int key0, int nkt, char* smem, f32x16 (&o)[2]) {
;     ...
;   lsum += __shfl_xor(lsum, 32);
;   float inv = 1.f / lsum;
; #pragma unroll
;   for (int i = 0; i < 16; ++i) { o[0][i] = accO[0][i] * inv; o[1][i] = accO[1][i] * inv; }
; DI void store_o(bfr* O, int m, int colbase, int h, const f32x16 (&o)[2]) {
; #pragma unroll
;   for (int dt = 0; dt < 2; ++dt)
; #pragma unroll
;     for (int g4 = 0; g4 < 4; ++g4) {
;       int dv = dt * 32 + 8 * g4 + 4 * h;
;       uint2 pk; pk.x = pack2(o[dt][4 * g4], o[dt][4 * g4 + 1]); pk.y = pack2(o[dt][4 * g4 + 2], o[dt][4 * g4 + 3]);
;       *(uint2*)(O + (size_t)m * DM + colbase + dv) = pk;
;     }
	v_mfma_f32_32x32x16_bf16 v[16:31], v[36:39], v[32:35], v[16:31]
	v_lshl_add_u32 v36, v103, 1, v67
	v_lshl_add_u32 v38, v102, 1, v67
	ds_read_b64 v[36:37], v36 offset:27648
	ds_read_b64 v[38:39], v38 offset:27648
	v_exp_f32_e32 v58, v58
	v_exp_f32_e32 v59, v59
	v_exp_f32_e32 v60, v60
	s_waitcnt lgkmcnt(0)
	v_mfma_f32_32x32x16_bf16 v[0:15], v[36:39], v[32:35], v[0:15]
	v_lshl_add_u32 v36, v100, 1, v80
	v_lshl_add_u32 v38, v101, 1, v80
	v_exp_f32_e32 v61, v61
	v_exp_f32_e32 v62, v62
	v_exp_f32_e32 v63, v63
	v_cvt_pk_bf16_f32 v32, v56, v57
	v_cvt_pk_bf16_f32 v33, v58, v59
	v_cvt_pk_bf16_f32 v34, v60, v61
	v_cvt_pk_bf16_f32 v35, v62, v63
	ds_read_b64 v[36:37], v36 offset:27648
	ds_read_b64 v[38:39], v38 offset:27648
	v_add_f32_e32 v65, v55, v65
	v_add_f32_e32 v65, v40, v65
	v_add_f32_e32 v65, v56, v65
	v_add_f32_e32 v65, v41, v65
	v_add_f32_e32 v65, v57, v65
	v_add_f32_e32 v65, v42, v65
	v_add_f32_e32 v65, v58, v65
	v_add_f32_e32 v65, v43, v65
	v_add_f32_e32 v65, v59, v65
	s_waitcnt lgkmcnt(0)
	v_mfma_f32_32x32x16_bf16 v[16:31], v[36:39], v[32:35], v[16:31]
	v_lshl_add_u32 v36, v99, 1, v67
	v_lshl_add_u32 v38, v98, 1, v67
	v_add_f32_e32 v65, v44, v65
	ds_read_b64 v[36:37], v36 offset:27648
	ds_read_b64 v[38:39], v38 offset:27648
	v_add_f32_e32 v65, v60, v65
	v_add_f32_e32 v65, v45, v65
	v_add_f32_e32 v65, v61, v65
	v_add_f32_e32 v65, v46, v65
	v_add_f32_e32 v65, v62, v65
	v_add_f32_e32 v65, v47, v65
	v_add_f32_e32 v65, v63, v65
	v_fmac_f32_e32 v65, v113, v64
	s_waitcnt lgkmcnt(0)
	v_mfma_f32_32x32x16_bf16 v[0:15], v[36:39], v[32:35], v[0:15]
	ds_bpermute_b32 v32, v91, v65
	s_waitcnt lgkmcnt(0)
	v_add_f32_e32 v32, v65, v32
	v_div_scale_f32 v33, s[8:9], v32, v32, 1.0
	v_rcp_f32_e32 v34, v33
	s_load_dwordx4 s[8:11], s[0:1], 0x100
	s_waitcnt lgkmcnt(0)
	s_mov_b64 s[8:9], 0x2b7c700
	v_fma_f32 v35, -v33, v34, 1.0
	v_fmac_f32_e32 v34, v35, v34
	v_div_scale_f32 v35, vcc, 1.0, v32, 1.0
	v_mul_f32_e32 v36, v35, v34
	v_fma_f32 v37, -v33, v36, v35
	v_fmac_f32_e32 v36, v37, v34
	v_fma_f32 v33, -v33, v36, v35
	v_div_fmas_f32 v33, v33, v34, v36
	v_div_fixup_f32 v32, v33, v32, 1.0
	v_mul_f32_e32 v33, v0, v32
	v_and_or_b32 v0, v89, 31, v97
	v_mul_f32_e32 v34, v1, v32
	v_ashrrev_i32_e32 v1, 31, v0
	v_lshlrev_b64 v[0:1], 11, v[0:1]
	v_mul_f32_e32 v37, v4, v32
	v_lshl_add_u64 v[0:1], s[10:11], 0, v[0:1]
	v_lshrrev_b32_e32 v4, 2, v89
	v_lshl_add_u64 v[0:1], v[0:1], 0, v[152:153]
	v_and_b32_e32 v152, 8, v4
	v_lshl_add_u64 v[0:1], v[0:1], 0, v[152:153]
	v_mul_f32_e32 v38, v5, v32
	v_lshl_add_u64 v[4:5], v[0:1], 0, s[8:9]
	s_mov_b32 s8, 0x2b7c000
	v_add_co_u32_e32 v0, vcc, s8, v0
	v_mul_f32_e32 v16, v16, v32
	s_nop 0
	v_addc_co_u32_e32 v1, vcc, 0, v1, vcc
	v_mul_f32_e32 v17, v17, v32
	v_mul_f32_e32 v18, v18, v32
	v_mul_f32_e32 v35, v2, v32
	v_mul_f32_e32 v19, v19, v32
	v_mul_f32_e32 v36, v3, v32
	v_mul_f32_e32 v20, v20, v32
	v_mul_f32_e32 v21, v21, v32
	v_mul_f32_e32 v22, v22, v32
	v_mul_f32_e32 v23, v23, v32
	v_cvt_pk_bf16_f32 v2, v16, v17
	v_cvt_pk_bf16_f32 v3, v18, v19
	global_store_dwordx2 v[0:1], v[2:3], off offset:1792
	v_cvt_pk_bf16_f32 v0, v20, v21
	v_cvt_pk_bf16_f32 v1, v22, v23
	v_mul_f32_e32 v24, v24, v32
	v_mul_f32_e32 v25, v25, v32
	v_mul_f32_e32 v26, v26, v32
	v_mul_f32_e32 v27, v27, v32
	global_store_dwordx2 v[4:5], v[0:1], off offset:16
	v_cvt_pk_bf16_f32 v0, v24, v25
	v_cvt_pk_bf16_f32 v1, v26, v27
	v_mul_f32_e32 v28, v28, v32
	v_mul_f32_e32 v29, v29, v32
	v_mul_f32_e32 v30, v30, v32
	v_mul_f32_e32 v31, v31, v32
	global_store_dwordx2 v[4:5], v[0:1], off offset:32
	v_cvt_pk_bf16_f32 v0, v28, v29
	v_cvt_pk_bf16_f32 v1, v30, v31
	global_store_dwordx2 v[4:5], v[0:1], off offset:48
	v_cvt_pk_bf16_f32 v0, v33, v34
	v_cvt_pk_bf16_f32 v1, v35, v36
	v_mul_f32_e32 v6, v6, v32
	v_mul_f32_e32 v7, v7, v32
	global_store_dwordx2 v[4:5], v[0:1], off offset:64
	v_cvt_pk_bf16_f32 v0, v37, v38
	v_cvt_pk_bf16_f32 v1, v6, v7
	v_mul_f32_e32 v8, v8, v32
	v_mul_f32_e32 v9, v9, v32
	v_mul_f32_e32 v10, v10, v32
	v_mul_f32_e32 v11, v11, v32
	global_store_dwordx2 v[4:5], v[0:1], off offset:80
	v_cvt_pk_bf16_f32 v0, v8, v9
	v_cvt_pk_bf16_f32 v1, v10, v11
	v_mul_f32_e32 v12, v12, v32
	v_mul_f32_e32 v13, v13, v32
	v_mul_f32_e32 v14, v14, v32
	v_mul_f32_e32 v15, v15, v32
	global_store_dwordx2 v[4:5], v[0:1], off offset:96
	v_cvt_pk_bf16_f32 v0, v12, v13
	v_cvt_pk_bf16_f32 v1, v14, v15
	global_store_dwordx2 v[4:5], v[0:1], off offset:112
